# attention 64-dim main loop: QK issued as s0 chain then s1 chain, the 16 exps of s0 placed in the s1 MFMA gaps, V fragment reads moved into the chain
# speedup vs baseline: 1.0623x; 1.0039x over previous
.LBB0_336:
	global_load_dwordx4 v[104:107], v[190:191], off
	global_load_dwordx4 v[96:99], v[192:193], off
	s_waitcnt lgkmcnt(2)
	v_mfma_f32_32x32x16_bf16 v[64:79], v[160:163], v[80:83], v[32:47]
	s_mov_b32 s8, s33
	v_mfma_f32_32x32x16_bf16 v[64:79], v[156:159], v[84:87], v[64:79]
	v_mfma_f32_32x32x16_bf16 v[64:79], v[144:147], v[92:95], v[64:79]
	v_mfma_f32_32x32x16_bf16 v[64:79], v[140:143], v[88:91], v[64:79]
	v_mfma_f32_32x32x16_bf16 v[48:63], v[164:167], v[80:83], v[32:47]
	s_and_b32 s33, 1, s76
	s_cselect_b32 s9, 0, 0x2400
	v_add_u32_e32 v100, s9, v199
	ds_read_b128 v[128:131], v100 offset:18432
	ds_read_b128 v[116:119], v100 offset:18464
	ds_read_b128 v[132:135], v100 offset:23040
	ds_read_b128 v[120:123], v100 offset:23072
	ds_read_b128 v[112:115], v100 offset:18496
	ds_read_b128 v[108:111], v100 offset:18528
	ds_read_b128 v[124:127], v100 offset:23104
	ds_read_b128 v[100:103], v100 offset:23136
	v_mfma_f32_32x32x16_bf16 v[48:63], v[152:155], v[84:87], v[48:63]
	v_exp_f32_e32 v64, v64
	v_exp_f32_e32 v65, v65
	v_exp_f32_e32 v66, v66
	v_mfma_f32_32x32x16_bf16 v[48:63], v[148:151], v[92:95], v[48:63]
	v_exp_f32_e32 v67, v67
	v_exp_f32_e32 v68, v68
	v_exp_f32_e32 v69, v69
	v_mfma_f32_32x32x16_bf16 v[48:63], v[136:139], v[88:91], v[48:63]
	v_exp_f32_e32 v70, v70
	v_exp_f32_e32 v71, v71
	v_exp_f32_e32 v72, v72
	v_exp_f32_e32 v73, v73
	v_exp_f32_e32 v74, v74
	v_exp_f32_e32 v75, v75
	v_exp_f32_e32 v76, v76
	v_exp_f32_e32 v77, v77
	v_exp_f32_e32 v78, v78
	v_exp_f32_e32 v79, v79
	s_setprio 0
	s_nop 0
.LBB0_338:
	v_exp_f32_e32 v219, v48
	v_exp_f32_e32 v220, v49
	v_exp_f32_e32 v221, v50
	v_exp_f32_e32 v222, v51
	v_exp_f32_e32 v223, v52
	v_exp_f32_e32 v224, v53
	v_exp_f32_e32 v225, v54
	v_exp_f32_e32 v226, v55
	s_cmp_eq_u32 s98, 0
	s_cbranch_scc1 .Lstg_x_3
	s_waitcnt lgkmcnt(0)
	s_barrier
.Lstg_x_3:
	v_exp_f32_e32 v227, v56
	v_exp_f32_e32 v228, v57
	v_exp_f32_e32 v229, v58
	v_exp_f32_e32 v230, v59
	v_exp_f32_e32 v231, v60
	v_exp_f32_e32 v232, v61
	v_exp_f32_e32 v233, v62
	v_exp_f32_e32 v234, v63
	v_cvt_pk_bf16_f32 v48, v64, v65
	v_cvt_pk_bf16_f32 v49, v66, v67
	v_cvt_pk_bf16_f32 v50, v68, v69
	v_cvt_pk_bf16_f32 v51, v70, v71
	v_cvt_pk_bf16_f32 v52, v72, v73
	v_cvt_pk_bf16_f32 v53, v74, v75
	v_cvt_pk_bf16_f32 v54, v76, v77
	v_cvt_pk_bf16_f32 v55, v78, v79
	v_cvt_pk_bf16_f32 v56, v219, v220
	v_cvt_pk_bf16_f32 v57, v221, v222
	v_cvt_pk_bf16_f32 v58, v223, v224
	v_cvt_pk_bf16_f32 v59, v225, v226
	v_cvt_pk_bf16_f32 v60, v227, v228
	v_cvt_pk_bf16_f32 v61, v229, v230
	v_cvt_pk_bf16_f32 v62, v231, v232
	v_cvt_pk_bf16_f32 v63, v233, v234
	s_setprio 1
	s_cmp_lg_u32 s98, 0
	s_cbranch_scc1 .Lstg_y_4
	s_waitcnt lgkmcnt(0)
	s_barrier
